# adds: norm/modulate phases (P2 via LDS-DMA row buffer, P8 via spare registers) request the next prompt row of a wave while the current row is processed
# speedup vs baseline: 1.0125x; 1.0125x over previous
; #define LAS __attribute__((address_space(3)))
; template <bool GATES>
; __device__ __forceinline__ void norm_mod_phase(const Frame& F, const float* src0, const float* src1, const float* nw, int sh_off, int sc_off, int nparts, float* x1out) {
;     const float* mod = (const float*)(F.ws + WS_MOD);
;     bf16_t* H = (bf16_t*)(F.ws + WS_H);
;     LAS float* wg = (LAS float*)F.lds;
;     if (GATES) { const f32x4* s = (const f32x4*)(F.ws + WS_WG); for (int i = F.tid; i < 8 * D / 4; i += 512) ((LAS f32x4*)wg)[i] = s[i]; __syncthreads(); }
;     f32x4 av[8], shv[8];
;     { const float* mr = mod + (size_t)128 * NMOD;
; #pragma unroll
;       for (int i = 0; i < 8; ++i) { const int c4 = i * 64 + F.lane; const f32x4 w = ((const f32x4*)nw)[c4], sc = ((const f32x4*)(mr + sc_off))[c4]; shv[i] = ((const f32x4*)(mr + sh_off))[c4]; av[i] = w * (sc + 1.f); } }
;     for (int r = F.bid * 8 + F.wave; r < MTOT; r += F.G * 8) {
;         const float* xr = r < SP ? src0 + (size_t)r * D : src1 + (size_t)(r - SP) * D;
;         f32x4 xv[8]; float ss = 0.f;
; #pragma unroll
;         for (int i = 0; i < 8; ++i) xv[i] = ((const f32x4*)xr)[i * 64 + F.lane];
.LBB0_196:
	s_or_b64 exec, exec, s[2:3]
	s_lshl_b32 s2, s33, 3
	s_add_i32 s6, s2, s80
	s_cmpk_lt_i32 s6, 0x2200
	s_waitcnt lgkmcnt(0)
	s_barrier
	s_cbranch_scc0 .LBB0_203
	s_load_dwordx16 s[8:23], s[0:1], 0x40
	s_waitcnt lgkmcnt(0)
	s_add_u32 s8, s84, 0x9702000
	s_addc_u32 s9, s85, 0
	v_or_b32_e32 v32, 0x1c0, v160
	s_add_u32 s2, s84, 0x9700000
	v_mov_b32_e32 v35, 0
	v_lshlrev_b32_e32 v34, 4, v32
	s_addc_u32 s3, s85, 0
	v_or_b32_e32 v36, 0x180, v160
	v_or_b32_e32 v110, 0xc0, v160
	v_or_b32_e32 v112, 0x80, v160
	v_or_b32_e32 v130, 64, v160
	v_lshl_add_u64 v[66:67], s[10:11], 0, v[34:35]
	global_load_dwordx4 v[38:41], v34, s[10:11]
	global_load_dwordx4 v[42:45], v34, s[8:9]
	global_load_dwordx4 v[0:3], v34, s[2:3]
	v_lshlrev_b32_e32 v34, 4, v36
	v_lshlrev_b32_e32 v16, 4, v110
	v_lshlrev_b32_e32 v20, 4, v112
	v_lshlrev_b32_e32 v24, 4, v130
	v_or_b32_e32 v132, 0x140, v160
	v_lshl_add_u64 v[68:69], s[10:11], 0, v[34:35]
	global_load_dwordx4 v[46:49], v16, s[8:9]
	global_load_dwordx4 v[50:53], v20, s[8:9]
	global_load_dwordx4 v[54:57], v24, s[8:9]
	global_load_dwordx4 v[58:61], v34, s[10:11]
	global_load_dwordx4 v[62:65], v34, s[8:9]
	global_load_dwordx4 v[4:7], v34, s[2:3]
	v_lshlrev_b32_e32 v34, 4, v132
	v_or_b32_e32 v134, 0x100, v160
	v_lshl_add_u64 v[70:71], s[10:11], 0, v[34:35]
	global_load_dwordx4 v[88:91], v34, s[10:11]
	global_load_dwordx4 v[92:95], v34, s[8:9]
	global_load_dwordx4 v[8:11], v34, s[2:3]
	v_lshlrev_b32_e32 v34, 4, v134
	global_load_dwordx4 v[98:101], v34, s[10:11]
	global_load_dwordx4 v[102:105], v34, s[8:9]
	v_lshl_add_u64 v[72:73], s[10:11], 0, v[34:35]
	global_load_dwordx4 v[12:15], v34, s[2:3]
	v_lshlrev_b32_e32 v34, 4, v160
	global_load_dwordx4 v[106:109], v34, s[10:11] offset:3072
	global_load_dwordx4 v[114:117], v34, s[10:11] offset:2048
	global_load_dwordx4 v[118:121], v34, s[10:11] offset:1024
	global_load_dwordx4 v[122:125], v34, s[8:9]
	global_load_dwordx4 v[126:129], v34, s[10:11]
	v_mbcnt_lo_u32_b32 v17, -1, 0
	v_mbcnt_hi_u32_b32 v33, -1, v17
	global_load_dwordx4 v[16:19], v16, s[2:3]
	s_nop 0
	global_load_dwordx4 v[20:23], v20, s[2:3]
	s_nop 0
	global_load_dwordx4 v[24:27], v24, s[2:3]
	s_nop 0
	global_load_dwordx4 v[28:31], v34, s[2:3]
	v_and_b32_e32 v37, 64, v33
	v_xor_b32_e32 v74, 32, v33
	v_add_u32_e32 v37, 64, v37
	v_xor_b32_e32 v76, 16, v33
	v_cmp_lt_i32_e32 vcc, v74, v37
	s_lshl_b32 s8, s88, 3
	s_ashr_i32 s7, s6, 31
	v_cndmask_b32_e32 v74, v33, v74, vcc
	v_cmp_lt_i32_e32 vcc, v76, v37
	v_lshlrev_b32_e32 v113, 2, v74
	v_lshl_add_u64 v[74:75], s[10:11], 0, v[34:35]
	v_cndmask_b32_e32 v35, v33, v76, vcc
	s_lshl_b64 s[10:11], s[6:7], 12
	s_ashr_i32 s9, s8, 31
	v_add_u32_e32 v152, 0, v34
	v_cmp_eq_u32_e64 s[2:3], 0, v160
	v_lshl_or_b32 v76, v160, 3, s10
	v_mov_b32_e32 v77, s11
	s_lshl_b64 s[10:11], s[8:9], 12
	s_lshl_b64 s[12:13], s[6:7], 5
	s_lshl_b64 s[14:15], s[8:9], 5
	v_lshlrev_b32_e32 v153, 4, v134
	v_lshlrev_b32_e32 v154, 4, v132
	v_lshlrev_b32_e32 v155, 4, v36
	v_lshlrev_b32_e32 v156, 4, v32
	v_lshlrev_b32_e32 v157, 4, v130
	v_lshlrev_b32_e32 v158, 4, v112
	v_lshlrev_b32_e32 v159, 4, v110
	v_mov_b32_e32 v161, 0x358637bd
	s_mov_b32 s20, 0x800000
	s_mov_b32 s21, 0x970c000
	v_mov_b32_e32 v162, 0xb90c000
	s_waitcnt vmcnt(22)
	v_pk_add_f32 v[44:45], v[44:45], 1.0 op_sel_hi:[1,0]
	v_pk_add_f32 v[42:43], v[42:43], 1.0 op_sel_hi:[1,0]
	v_pk_mul_f32 v[80:81], v[40:41], v[44:45]
	v_pk_mul_f32 v[84:85], v[38:39], v[42:43]
	s_waitcnt vmcnt(18)
	v_pk_add_f32 v[56:57], v[56:57], 1.0 op_sel_hi:[1,0]
	v_pk_add_f32 v[46:47], v[46:47], 1.0 op_sel_hi:[1,0]
	s_waitcnt vmcnt(16)
	v_pk_add_f32 v[40:41], v[62:63], 1.0 op_sel_hi:[1,0]
	v_pk_add_f32 v[38:39], v[64:65], 1.0 op_sel_hi:[1,0]
	v_pk_mul_f32 v[82:83], v[58:59], v[40:41]
	v_pk_mul_f32 v[78:79], v[60:61], v[38:39]
	s_waitcnt vmcnt(13)
	v_pk_add_f32 v[40:41], v[92:93], 1.0 op_sel_hi:[1,0]
	v_pk_add_f32 v[38:39], v[94:95], 1.0 op_sel_hi:[1,0]
	v_pk_mul_f32 v[88:89], v[88:89], v[40:41]
	s_waitcnt vmcnt(10)
	v_pk_add_f32 v[40:41], v[102:103], 1.0 op_sel_hi:[1,0]
	v_pk_mul_f32 v[86:87], v[90:91], v[38:39]
	v_pk_add_f32 v[38:39], v[104:105], 1.0 op_sel_hi:[1,0]
	v_pk_mul_f32 v[104:105], v[98:99], v[40:41]
	s_waitcnt vmcnt(5)
	v_pk_add_f32 v[40:41], v[122:123], 1.0 op_sel_hi:[1,0]
	v_lshlrev_b32_e32 v123, 2, v35
	v_xor_b32_e32 v35, 8, v33
	v_cmp_lt_i32_e32 vcc, v35, v37
	v_pk_mul_f32 v[96:97], v[100:101], v[38:39]
	v_pk_add_f32 v[38:39], v[124:125], 1.0 op_sel_hi:[1,0]
	v_cndmask_b32_e32 v35, v33, v35, vcc
	v_pk_mul_f32 v[102:103], v[106:107], v[46:47]
	s_waitcnt vmcnt(4)
	v_pk_mul_f32 v[106:107], v[128:129], v[38:39]
	v_lshlrev_b32_e32 v129, 2, v35
	v_xor_b32_e32 v35, 4, v33
	v_cmp_lt_i32_e32 vcc, v35, v37
	v_pk_add_f32 v[48:49], v[48:49], 1.0 op_sel_hi:[1,0]
	v_pk_add_f32 v[52:53], v[52:53], 1.0 op_sel_hi:[1,0]
	v_cndmask_b32_e32 v35, v33, v35, vcc
	v_lshlrev_b32_e32 v131, 2, v35
	v_xor_b32_e32 v35, 2, v33
	v_cmp_lt_i32_e32 vcc, v35, v37
	v_pk_add_f32 v[50:51], v[50:51], 1.0 op_sel_hi:[1,0]
	v_pk_add_f32 v[54:55], v[54:55], 1.0 op_sel_hi:[1,0]
	v_cndmask_b32_e32 v35, v33, v35, vcc
	v_lshlrev_b32_e32 v145, 2, v35
	v_xor_b32_e32 v35, 1, v33
	v_cmp_lt_i32_e32 vcc, v35, v37
	v_pk_mul_f32 v[94:95], v[108:109], v[48:49]
	v_pk_mul_f32 v[92:93], v[116:117], v[52:53]
	v_cndmask_b32_e32 v33, v33, v35, vcc
	v_pk_mul_f32 v[100:101], v[114:115], v[50:51]
	v_pk_mul_f32 v[90:91], v[120:121], v[56:57]
	v_pk_mul_f32 v[98:99], v[118:119], v[54:55]
	v_pk_mul_f32 v[108:109], v[126:127], v[40:41]
	v_lshlrev_b32_e32 v147, 2, v33
	s_load_dwordx2 s[66:67], s[0:1], 0x0
	s_lshl_b32 s58, s80, 13
	s_add_i32 s58, s58, 0x10000
	v_lshlrev_b32_e32 v224, 4, v160
	v_add_u32_e32 v225, s58, v224
	s_waitcnt lgkmcnt(0)
	s_branch .LBB0_199
; template <bool GATES>
; __device__ __forceinline__ void norm_mod_phase(const Frame& F, const float* src0, const float* src1, const float* nw, int sh_off, int sc_off, int nparts, float* x1out) {
;     ...
;     for (int r = F.bid * 8 + F.wave; r < MTOT; r += F.G * 8) {
;         const float* xr = r < SP ? src0 + (size_t)r * D : src1 + (size_t)(r - SP) * D;
;         f32x4 xv[8]; float ss = 0.f;
; #pragma unroll
;         for (int i = 0; i < 8; ++i) xv[i] = ((const f32x4*)xr)[i * 64 + F.lane];
;         if (r >= SP) { const float* mr = mod + (size_t)((r - SP) >> 2) * NMOD;
; #pragma unroll
;             for (int i = 0; i < 8; ++i) { const int c4 = i * 64 + F.lane; const f32x4 w = ((const f32x4*)nw)[c4], sc = ((const f32x4*)(mr + sc_off))[c4]; shv[i] = ((const f32x4*)(mr + sh_off))[c4]; av[i] = w * (sc + 1.f); }
;             if (nparts > 0) {
;                 for (int z = 0; z < nparts; ++z) { const f32x4* pp = (const f32x4*)(F.ws + WS_PART) + ((size_t)z * MS + (r - SP)) * (D / 4);
; #pragma unroll
;                     for (int i = 0; i < 8; ++i) xv[i] += pp[i * 64 + F.lane]; }
; #pragma unroll
;                 for (int i = 0; i < 8; ++i) ((f32x4*)(x1out + (size_t)(r - SP) * D))[i * 64 + F.lane] = xv[i]; } }
; #pragma unroll
;         for (int i = 0; i < 8; ++i) ss += xv[i][0] * xv[i][0] + xv[i][1] * xv[i][1] + xv[i][2] * xv[i][2] + xv[i][3] * xv[i][3];
.LBB0_198:
	s_or_b64 exec, exec, s[16:17]
	s_add_u32 s6, s6, s8
	s_addc_u32 s7, s7, s9
	s_add_u32 s12, s12, s14
	s_addc_u32 s13, s13, s15
	s_cmpk_lt_i32 s6, 0x2200
	v_lshl_add_u64 v[76:77], v[76:77], 0, s[10:11]
	s_cbranch_scc0 .LBB0_203
	s_cmpk_lt_i32 s6, 0x2000
	s_cbranch_scc0 .LBB0_199
	s_waitcnt vmcnt(10)
	ds_read_b128 v[60:63], v225
	ds_read_b128 v[56:59], v225 offset:1024
	ds_read_b128 v[52:55], v225 offset:2048
	ds_read_b128 v[48:51], v225 offset:3072
	ds_read_b128 v[44:47], v225 offset:4096
	ds_read_b128 v[40:43], v225 offset:5120
	ds_read_b128 v[36:39], v225 offset:6144
	ds_read_b128 v[32:35], v225 offset:7168
	s_waitcnt lgkmcnt(0)
	v_mul_f32_e32 v64, v61, v61
	v_mul_f32_e32 v65, v57, v57
	v_fmac_f32_e32 v64, v60, v60
	v_fmac_f32_e32 v65, v56, v56
	v_fmac_f32_e32 v64, v62, v62
	v_fmac_f32_e32 v65, v58, v58
	v_fmac_f32_e32 v64, v63, v63
	v_fmac_f32_e32 v65, v59, v59
	v_add_f32_e32 v64, v64, v65
	v_mul_f32_e32 v65, v53, v53
	v_fmac_f32_e32 v65, v52, v52
	v_fmac_f32_e32 v65, v54, v54
	v_fmac_f32_e32 v65, v55, v55
	v_add_f32_e32 v64, v64, v65
	v_mul_f32_e32 v65, v49, v49
	v_fmac_f32_e32 v65, v48, v48
	v_fmac_f32_e32 v65, v50, v50
	v_fmac_f32_e32 v65, v51, v51
	v_mov_b32_e32 v110, v45
	v_mov_b32_e32 v111, v41
	v_add_f32_e32 v112, v64, v65
	v_mov_b32_e32 v64, v44
	v_mov_b32_e32 v65, v40
	v_pk_mul_f32 v[110:111], v[110:111], v[110:111]
	s_nop 0
	v_pk_fma_f32 v[64:65], v[64:65], v[64:65], v[110:111]
	v_mov_b32_e32 v110, v46
	v_mov_b32_e32 v111, v42
	v_pk_fma_f32 v[64:65], v[110:111], v[110:111], v[64:65]
	v_mov_b32_e32 v110, v47
	v_mov_b32_e32 v111, v43
	v_pk_fma_f32 v[64:65], v[110:111], v[110:111], v[64:65]
	v_mov_b32_e32 v110, v37
	v_add_f32_e32 v64, v112, v64
	s_branch .Lmy_p2_join

; __device__ __forceinline__ unsigned cvt_pk_bf16(float lo, float hi) { unsigned r; asm volatile("v_cvt_pk_bf16_f32 %0, %1, %2" : "=v"(r) : "v"(lo), "v"(hi)); return r; }
; template <bool GATES>
; __device__ __forceinline__ void norm_mod_phase(const Frame& F, const float* src0, const float* src1, const float* nw, int sh_off, int sc_off, int nparts, float* x1out) {
;     ...
;         const float* xr = r < SP ? src0 + (size_t)r * D : src1 + (size_t)(r - SP) * D;
;         f32x4 xv[8]; float ss = 0.f;
; #pragma unroll
;         for (int i = 0; i < 8; ++i) xv[i] = ((const f32x4*)xr)[i * 64 + F.lane];
;         if (r >= SP) { const float* mr = mod + (size_t)((r - SP) >> 2) * NMOD;
; #pragma unroll
;             for (int i = 0; i < 8; ++i) { const int c4 = i * 64 + F.lane; const f32x4 w = ((const f32x4*)nw)[c4], sc = ((const f32x4*)(mr + sc_off))[c4]; shv[i] = ((const f32x4*)(mr + sh_off))[c4]; av[i] = w * (sc + 1.f); }
;             if (nparts > 0) {
;                 for (int z = 0; z < nparts; ++z) { const f32x4* pp = (const f32x4*)(F.ws + WS_PART) + ((size_t)z * MS + (r - SP)) * (D / 4);
; #pragma unroll
;                     for (int i = 0; i < 8; ++i) xv[i] += pp[i * 64 + F.lane]; }
; #pragma unroll
;                 for (int i = 0; i < 8; ++i) ((f32x4*)(x1out + (size_t)(r - SP) * D))[i * 64 + F.lane] = xv[i]; } }
; #pragma unroll
;         for (int i = 0; i < 8; ++i) ss += xv[i][0] * xv[i][0] + xv[i][1] * xv[i][1] + xv[i][2] * xv[i][2] + xv[i][3] * xv[i][3];
;         ss = wave_sum(ss);
;         const float rstd = rsqrtf(ss * (1.f / D) + EPS);
;         float g[8];
; #pragma unroll
;         for (int j = 0; j < 8; ++j) g[j] = 0.f;
; #pragma unroll
;         for (int i = 0; i < 8; ++i) { const int c4 = i * 64 + F.lane;
;             f32x4 h;
; #pragma unroll
;             for (int e = 0; e < 4; ++e) h[e] = (xv[i][e] * rstd) * av[i][e] + shv[i][e];
;             u32x2 pk; pk.x = cvt_pk_bf16(h[0], h[1]); pk.y = cvt_pk_bf16(h[2], h[3]);
;             *(u32x2*)(H + (size_t)r * D + c4 * 4) = pk;
.Lmy_p2_join:
	s_add_u32 s56, s6, s8
	s_cmpk_lt_i32 s56, 0x2000
	s_cbranch_scc0 .Lmy_p2_nopf
	s_mov_b32 s57, 0
	s_lshl_b64 s[56:57], s[56:57], 13
	s_add_u32 s56, s66, s56
	s_addc_u32 s57, s67, s57
	s_mov_b32 m0, s58
	s_nop 0
	global_load_lds_dwordx4 v224, s[56:57]
	global_load_lds_dwordx4 v224, s[56:57] offset:1024
	global_load_lds_dwordx4 v224, s[56:57] offset:2048
	global_load_lds_dwordx4 v224, s[56:57] offset:3072
	s_add_u32 s56, s56, 0x1000
	s_addc_u32 s57, s57, 0
	s_add_i32 m0, s58, 0x1000
	s_nop 0
	global_load_lds_dwordx4 v224, s[56:57]
	global_load_lds_dwordx4 v224, s[56:57] offset:1024
	global_load_lds_dwordx4 v224, s[56:57] offset:2048
	global_load_lds_dwordx4 v224, s[56:57] offset:3072
.Lmy_p2_nopf:
	v_mov_b32_e32 v111, v33
	v_add_f32_e32 v112, v64, v65
	v_mov_b32_e32 v64, v36
	v_mov_b32_e32 v65, v32
	v_pk_mul_f32 v[110:111], v[110:111], v[110:111]
	s_nop 0
	v_pk_fma_f32 v[64:65], v[64:65], v[64:65], v[110:111]
	v_mov_b32_e32 v110, v38
	v_mov_b32_e32 v111, v34
	v_pk_fma_f32 v[64:65], v[110:111], v[110:111], v[64:65]
	v_mov_b32_e32 v110, v39
	v_mov_b32_e32 v111, v35
	v_pk_fma_f32 v[64:65], v[110:111], v[110:111], v[64:65]
	s_nop 0
	v_add_f32_e32 v64, v112, v64
	v_add_f32_e32 v64, v64, v65
	ds_bpermute_b32 v65, v113, v64
	s_waitcnt lgkmcnt(0)
	v_add_f32_e32 v64, v64, v65
	ds_bpermute_b32 v65, v123, v64
	s_waitcnt lgkmcnt(0)
	v_add_f32_e32 v64, v64, v65
	ds_bpermute_b32 v65, v129, v64
	s_waitcnt lgkmcnt(0)
	v_add_f32_e32 v64, v64, v65
	ds_bpermute_b32 v65, v131, v64
	s_waitcnt lgkmcnt(0)
	v_add_f32_e32 v64, v64, v65
	ds_bpermute_b32 v65, v145, v64
	s_waitcnt lgkmcnt(0)
	v_add_f32_e32 v64, v64, v65
	ds_bpermute_b32 v65, v147, v64
	s_waitcnt lgkmcnt(0)
	v_add_f32_e32 v64, v64, v65
	v_fmamk_f32 v64, v64, 0x3a000000, v161
	v_mul_f32_e32 v65, 0x4b800000, v64
	v_cmp_gt_f32_e32 vcc, s20, v64
	s_nop 1
	v_cndmask_b32_e32 v64, v64, v65, vcc
	v_rsq_f32_e32 v64, v64
	s_nop 0
	v_mul_f32_e32 v65, 0x45800000, v64
	v_cndmask_b32_e32 v112, v64, v65, vcc
	v_mul_f32_e32 v62, v62, v112
	v_fma_f32 v64, v106, v62, v30
	v_mul_f32_e32 v62, v63, v112
	v_fma_f32 v122, v107, v62, v31
	v_lshl_add_u64 v[62:63], s[84:85], 0, v[76:77]
	v_add_co_u32_e32 v110, vcc, s21, v62
	v_pk_mul_f32 v[60:61], v[60:61], v[112:113] op_sel_hi:[1,0]
	s_nop 0
	v_addc_co_u32_e32 v111, vcc, 0, v63, vcc
	v_pk_fma_f32 v[188:189], v[108:109], v[60:61], v[28:29]
	v_mul_f32_e32 v58, v58, v112
	v_cvt_pk_bf16_f32 v60, v188, v189
	v_cvt_pk_bf16_f32 v61, v64, v122
	global_store_dwordx2 v[110:111], v[60:61], off
	ds_read_b128 v[60:63], v152
	ds_read_b128 v[114:117], v152 offset:8192
	ds_read_b128 v[118:121], v152 offset:49152
	ds_read_b128 v[124:127], v152 offset:57344
	ds_read_b128 v[132:135], v152 offset:16384
	ds_read_b128 v[136:139], v152 offset:24576
	ds_read_b128 v[140:143], v152 offset:32768
	ds_read_b128 v[148:151], v152 offset:40960
	s_waitcnt lgkmcnt(5)
	v_mov_b32_e32 v165, v119
	s_waitcnt lgkmcnt(4)
	v_pk_mov_b32 v[118:119], v[124:125], v[118:119] op_sel:[1,0]
	v_mov_b32_e32 v164, v124
	v_pk_mul_f32 v[118:119], v[118:119], v[188:189] op_sel:[0,1] op_sel_hi:[1,0]
	v_mov_b32_e32 v124, v126
	v_pk_fma_f32 v[118:119], v[164:165], v[188:189], v[118:119]
	v_mov_b32_e32 v125, v120
	v_pk_fma_f32 v[118:119], v[124:125], v[64:65], v[118:119] op_sel_hi:[1,0,1]
	v_mov_b32_e32 v120, v127
	v_fma_f32 v128, v90, v58, v26
	v_mul_f32_e32 v58, v59, v112
	v_pk_fma_f32 v[118:119], v[120:121], v[122:123], v[118:119] op_sel_hi:[1,0,1]
	v_pk_mul_f32 v[56:57], v[56:57], v[112:113] op_sel_hi:[1,0]
	v_fma_f32 v130, v91, v58, v27
	v_pk_add_f32 v[190:191], v[118:119], 0 op_sel_hi:[1,0]
	v_pk_fma_f32 v[56:57], v[98:99], v[56:57], v[24:25]
	v_mul_f32_e32 v54, v54, v112
	v_cvt_pk_bf16_f32 v118, v56, v57
	v_cvt_pk_bf16_f32 v119, v128, v130
	global_store_dwordx2 v[110:111], v[118:119], off offset:512
	ds_read_b128 v[118:121], v152 offset:1024
	ds_read_b128 v[124:127], v152 offset:9216
	ds_read_b128 v[164:167], v152 offset:50176
	ds_read_b128 v[168:171], v152 offset:58368
	ds_read_b128 v[172:175], v152 offset:17408
	ds_read_b128 v[176:179], v152 offset:25600
	ds_read_b128 v[180:183], v152 offset:33792
	ds_read_b128 v[184:187], v152 offset:41984
	s_waitcnt lgkmcnt(5)
	v_mov_b32_e32 v193, v165
	s_waitcnt lgkmcnt(4)
	v_pk_mov_b32 v[164:165], v[168:169], v[164:165] op_sel:[1,0]
	v_mov_b32_e32 v192, v168
	v_pk_mul_f32 v[164:165], v[56:57], v[164:165] op_sel:[1,0] op_sel_hi:[0,1]
	v_pk_fma_f32 v[164:165], v[56:57], v[192:193], v[164:165]
	v_mov_b32_e32 v168, v170
	v_mov_b32_e32 v169, v166
	v_pk_fma_f32 v[164:165], v[128:129], v[168:169], v[164:165] op_sel_hi:[0,1,1]
	v_mov_b32_e32 v166, v171
	v_fma_f32 v58, v92, v54, v22
	v_mul_f32_e32 v54, v55, v112
	v_pk_fma_f32 v[164:165], v[130:131], v[166:167], v[164:165] op_sel_hi:[0,1,1]
	v_pk_mul_f32 v[52:53], v[52:53], v[112:113] op_sel_hi:[1,0]
	v_pk_mov_b32 v[192:193], v[60:61], v[114:115] op_sel:[1,0]
	v_mov_b32_e32 v61, v115
	v_fma_f32 v54, v93, v54, v23
	v_pk_add_f32 v[190:191], v[190:191], v[164:165]
	v_pk_fma_f32 v[52:53], v[100:101], v[52:53], v[20:21]
	v_pk_mul_f32 v[60:61], v[60:61], v[188:189]
	v_cvt_pk_bf16_f32 v164, v52, v53
	v_cvt_pk_bf16_f32 v165, v58, v54
	global_store_dwordx2 v[110:111], v[164:165], off offset:1024
	ds_read_b128 v[164:167], v152 offset:2048
	ds_read_b128 v[168:171], v152 offset:10240
	v_pk_fma_f32 v[60:61], v[192:193], v[188:189], v[60:61] op_sel:[0,1,0] op_sel_hi:[1,0,1]
	v_mov_b32_e32 v114, v62
	v_mov_b32_e32 v115, v116
	v_mov_b32_e32 v116, v63
	v_pk_mov_b32 v[62:63], v[118:119], v[124:125] op_sel:[1,0]
	v_mov_b32_e32 v119, v125
	v_pk_fma_f32 v[60:61], v[114:115], v[64:65], v[60:61] op_sel_hi:[1,0,1]
	v_pk_mul_f32 v[114:115], v[56:57], v[118:119]
	v_pk_fma_f32 v[60:61], v[116:117], v[122:123], v[60:61] op_sel_hi:[1,0,1]
	v_pk_fma_f32 v[62:63], v[56:57], v[62:63], v[114:115] op_sel:[1,0,0] op_sel_hi:[0,1,1]
	v_mov_b32_e32 v114, v120
	v_mov_b32_e32 v115, v126
	v_pk_fma_f32 v[62:63], v[128:129], v[114:115], v[62:63] op_sel_hi:[0,1,1]
	v_mov_b32_e32 v126, v121
	v_pk_add_f32 v[60:61], v[60:61], 0 op_sel_hi:[1,0]
	v_pk_fma_f32 v[62:63], v[130:131], v[126:127], v[62:63] op_sel_hi:[0,1,1]
	v_pk_add_f32 v[60:61], v[60:61], v[62:63]
	s_waitcnt lgkmcnt(0)
; #define LAS __attribute__((address_space(3)))
; __device__ __forceinline__ unsigned cvt_pk_bf16(float lo, float hi) { unsigned r; asm volatile("v_cvt_pk_bf16_f32 %0, %1, %2" : "=v"(r) : "v"(lo), "v"(hi)); return r; }
; template <bool GATES>
; __device__ __forceinline__ void norm_mod_phase(const Frame& F, const float* src0, const float* src1, const float* nw, int sh_off, int sc_off, int nparts, float* x1out) {
;     ...
;         for (int i = 0; i < 8; ++i) { const int c4 = i * 64 + F.lane;
;             f32x4 h;
; #pragma unroll
;             for (int e = 0; e < 4; ++e) h[e] = (xv[i][e] * rstd) * av[i][e] + shv[i][e];
;             u32x2 pk; pk.x = cvt_pk_bf16(h[0], h[1]); pk.y = cvt_pk_bf16(h[2], h[3]);
;             *(u32x2*)(H + (size_t)r * D + c4 * 4) = pk;
;             if (GATES) {
; #pragma unroll
;                 for (int j = 0; j < 8; ++j) { const f32x4 wv = ((const LAS f32x4*)(wg + j * D))[c4]; g[j] += h[0] * wv[0] + h[1] * wv[1] + h[2] * wv[2] + h[3] * wv[3]; } } }
	v_pk_mov_b32 v[62:63], v[164:165], v[168:169] op_sel:[1,0]
	v_mov_b32_e32 v165, v169
	v_pk_mul_f32 v[114:115], v[52:53], v[164:165]
	v_pk_mov_b32 v[118:119], v[132:133], v[136:137] op_sel:[1,0]
	v_pk_fma_f32 v[62:63], v[52:53], v[62:63], v[114:115] op_sel:[1,0,0] op_sel_hi:[0,1,1]
	v_mov_b32_e32 v114, v166
	v_mov_b32_e32 v115, v170
	v_mov_b32_e32 v133, v137
	v_pk_fma_f32 v[62:63], v[58:59], v[114:115], v[62:63] op_sel_hi:[0,1,1]
	v_mov_b32_e32 v170, v167
	v_pk_mul_f32 v[124:125], v[132:133], v[188:189]
	v_pk_fma_f32 v[62:63], v[54:55], v[170:171], v[62:63] op_sel_hi:[0,1,1]
	v_pk_fma_f32 v[118:119], v[118:119], v[188:189], v[124:125] op_sel:[0,1,0] op_sel_hi:[1,0,1]
	v_mov_b32_e32 v124, v134
	v_mov_b32_e32 v125, v138
	v_pk_add_f32 v[120:121], v[60:61], v[62:63]
	ds_read_b128 v[60:63], v152 offset:18432
	ds_read_b128 v[114:117], v152 offset:26624
	v_pk_fma_f32 v[118:119], v[124:125], v[64:65], v[118:119] op_sel_hi:[1,0,1]
	v_pk_mov_b32 v[124:125], v[172:173], v[176:177] op_sel:[1,0]
	v_mov_b32_e32 v173, v177
	v_pk_mul_f32 v[126:127], v[56:57], v[172:173]
	v_mov_b32_e32 v138, v135
	v_pk_fma_f32 v[124:125], v[56:57], v[124:125], v[126:127] op_sel:[1,0,0] op_sel_hi:[0,1,1]
	v_mov_b32_e32 v126, v174
	v_mov_b32_e32 v127, v178
	v_pk_fma_f32 v[118:119], v[138:139], v[122:123], v[118:119] op_sel_hi:[1,0,1]
	v_pk_fma_f32 v[124:125], v[128:129], v[126:127], v[124:125] op_sel_hi:[0,1,1]
	v_mov_b32_e32 v178, v175
	v_pk_add_f32 v[118:119], v[118:119], 0 op_sel_hi:[1,0]
	v_pk_fma_f32 v[124:125], v[130:131], v[178:179], v[124:125] op_sel_hi:[0,1,1]
	v_pk_add_f32 v[118:119], v[118:119], v[124:125]
	s_waitcnt lgkmcnt(0)
	v_pk_mov_b32 v[124:125], v[60:61], v[114:115] op_sel:[1,0]
	v_mov_b32_e32 v61, v115
	v_pk_mul_f32 v[60:61], v[52:53], v[60:61]
	v_mov_b32_e32 v114, v62
	v_pk_fma_f32 v[60:61], v[52:53], v[124:125], v[60:61] op_sel:[1,0,0] op_sel_hi:[0,1,1]
	v_mov_b32_e32 v115, v116
	v_pk_mov_b32 v[124:125], v[140:141], v[148:149] op_sel:[1,0]
	v_mov_b32_e32 v141, v149
	v_pk_fma_f32 v[60:61], v[58:59], v[114:115], v[60:61] op_sel_hi:[0,1,1]
	v_mov_b32_e32 v116, v63
	v_pk_mul_f32 v[126:127], v[140:141], v[188:189]
	v_pk_fma_f32 v[60:61], v[54:55], v[116:117], v[60:61] op_sel_hi:[0,1,1]
	v_pk_fma_f32 v[124:125], v[124:125], v[188:189], v[126:127] op_sel:[0,1,0] op_sel_hi:[1,0,1]
	v_mov_b32_e32 v126, v142
	v_mov_b32_e32 v127, v150
	v_pk_add_f32 v[118:119], v[118:119], v[60:61]
	ds_read_b128 v[60:63], v152 offset:34816
	ds_read_b128 v[114:117], v152 offset:43008
	v_pk_fma_f32 v[64:65], v[126:127], v[64:65], v[124:125] op_sel_hi:[1,0,1]
	v_pk_mov_b32 v[124:125], v[180:181], v[184:185] op_sel:[1,0]
	v_mov_b32_e32 v181, v185
	v_pk_mul_f32 v[126:127], v[56:57], v[180:181]
	v_mov_b32_e32 v150, v143
	v_pk_fma_f32 v[56:57], v[56:57], v[124:125], v[126:127] op_sel:[1,0,0] op_sel_hi:[0,1,1]
	v_mov_b32_e32 v124, v182
	v_mov_b32_e32 v125, v186
	v_pk_fma_f32 v[64:65], v[150:151], v[122:123], v[64:65] op_sel_hi:[1,0,1]
	v_pk_fma_f32 v[56:57], v[128:129], v[124:125], v[56:57] op_sel_hi:[0,1,1]
	v_mov_b32_e32 v186, v183
	v_pk_add_f32 v[64:65], v[64:65], 0 op_sel_hi:[1,0]
	v_pk_fma_f32 v[56:57], v[130:131], v[186:187], v[56:57] op_sel_hi:[0,1,1]
	v_pk_add_f32 v[56:57], v[64:65], v[56:57]
	s_waitcnt lgkmcnt(0)
	v_pk_mov_b32 v[64:65], v[60:61], v[114:115] op_sel:[1,0]
	v_mov_b32_e32 v61, v115
	ds_read_b128 v[124:127], v152 offset:51200
	ds_read_b128 v[132:135], v152 offset:59392
	v_pk_mul_f32 v[60:61], v[52:53], v[60:61]
	v_mul_f32_e32 v50, v50, v112
	v_pk_fma_f32 v[60:61], v[52:53], v[64:65], v[60:61] op_sel:[1,0,0] op_sel_hi:[0,1,1]
	v_mov_b32_e32 v64, v62
	v_mov_b32_e32 v65, v116
	v_pk_fma_f32 v[60:61], v[58:59], v[64:65], v[60:61] op_sel_hi:[0,1,1]
	v_mov_b32_e32 v116, v63
	v_pk_fma_f32 v[60:61], v[54:55], v[116:117], v[60:61] op_sel_hi:[0,1,1]
	v_pk_add_f32 v[116:117], v[56:57], v[60:61]
	s_waitcnt lgkmcnt(0)
	v_pk_mov_b32 v[60:61], v[132:133], v[124:125] op_sel:[1,0]
	v_mov_b32_e32 v56, v132
	v_mov_b32_e32 v57, v125
	v_pk_mul_f32 v[60:61], v[52:53], v[60:61] op_sel:[1,0] op_sel_hi:[0,1]
	v_pk_fma_f32 v[52:53], v[52:53], v[56:57], v[60:61]
	v_mov_b32_e32 v56, v134
	v_mov_b32_e32 v57, v126
	v_fma_f32 v124, v94, v50, v18
	v_mul_f32_e32 v50, v51, v112
	v_pk_mul_f32 v[48:49], v[48:49], v[112:113] op_sel_hi:[1,0]
	v_pk_fma_f32 v[52:53], v[58:59], v[56:57], v[52:53] op_sel_hi:[0,1,1]
	v_fma_f32 v128, v95, v50, v19
	v_pk_fma_f32 v[64:65], v[102:103], v[48:49], v[16:17]
	v_mov_b32_e32 v126, v135
	v_cvt_pk_bf16_f32 v60, v64, v65
	v_cvt_pk_bf16_f32 v61, v124, v128
	ds_read_b128 v[48:51], v152 offset:3072
	ds_read_b128 v[56:59], v152 offset:11264
	v_pk_fma_f32 v[52:53], v[54:55], v[126:127], v[52:53] op_sel_hi:[0,1,1]
	v_pk_add_f32 v[114:115], v[190:191], v[52:53]
	global_store_dwordx2 v[110:111], v[60:61], off offset:1536
	v_mul_f32_e32 v46, v46, v112
	s_waitcnt lgkmcnt(0)
	v_pk_mov_b32 v[52:53], v[48:49], v[56:57] op_sel:[1,0]
	v_mov_b32_e32 v49, v57
	v_pk_mul_f32 v[48:49], v[64:65], v[48:49]
	v_mov_b32_e32 v56, v50
	v_pk_fma_f32 v[48:49], v[64:65], v[52:53], v[48:49] op_sel:[1,0,0] op_sel_hi:[0,1,1]
	ds_read_b128 v[52:55], v152 offset:19456
	ds_read_b128 v[60:63], v152 offset:27648
	v_mov_b32_e32 v57, v58
	v_pk_fma_f32 v[48:49], v[124:125], v[56:57], v[48:49] op_sel_hi:[0,1,1]
	v_mov_b32_e32 v58, v51
	v_pk_fma_f32 v[138:139], v[128:129], v[58:59], v[48:49] op_sel_hi:[0,1,1]
	s_waitcnt lgkmcnt(0)
	v_pk_mov_b32 v[48:49], v[52:53], v[60:61] op_sel:[1,0]
	v_mov_b32_e32 v53, v61
	v_pk_mul_f32 v[50:51], v[64:65], v[52:53]
	v_mov_b32_e32 v60, v54
	v_pk_fma_f32 v[52:53], v[64:65], v[48:49], v[50:51] op_sel:[1,0,0] op_sel_hi:[0,1,1]
	ds_read_b128 v[48:51], v152 offset:35840
	ds_read_b128 v[56:59], v152 offset:44032
	v_mov_b32_e32 v61, v62
	v_pk_fma_f32 v[52:53], v[124:125], v[60:61], v[52:53] op_sel_hi:[0,1,1]
	v_mov_b32_e32 v62, v55
	v_pk_fma_f32 v[132:133], v[128:129], v[62:63], v[52:53] op_sel_hi:[0,1,1]
	s_waitcnt lgkmcnt(0)
; #define LAS __attribute__((address_space(3)))
; __device__ __forceinline__ unsigned cvt_pk_bf16(float lo, float hi) { unsigned r; asm volatile("v_cvt_pk_bf16_f32 %0, %1, %2" : "=v"(r) : "v"(lo), "v"(hi)); return r; }
; template <bool GATES>
; __device__ __forceinline__ void norm_mod_phase(const Frame& F, const float* src0, const float* src1, const float* nw, int sh_off, int sc_off, int nparts, float* x1out) {
;     ...
;         for (int i = 0; i < 8; ++i) { const int c4 = i * 64 + F.lane;
;             f32x4 h;
; #pragma unroll
;             for (int e = 0; e < 4; ++e) h[e] = (xv[i][e] * rstd) * av[i][e] + shv[i][e];
;             u32x2 pk; pk.x = cvt_pk_bf16(h[0], h[1]); pk.y = cvt_pk_bf16(h[2], h[3]);
;             *(u32x2*)(H + (size_t)r * D + c4 * 4) = pk;
;             if (GATES) {
; #pragma unroll
;                 for (int j = 0; j < 8; ++j) { const f32x4 wv = ((const LAS f32x4*)(wg + j * D))[c4]; g[j] += h[0] * wv[0] + h[1] * wv[1] + h[2] * wv[2] + h[3] * wv[3]; } } }
	v_pk_mov_b32 v[52:53], v[48:49], v[56:57] op_sel:[1,0]
	v_mov_b32_e32 v49, v57
	v_pk_mul_f32 v[48:49], v[64:65], v[48:49]
	v_mov_b32_e32 v56, v50
	v_pk_fma_f32 v[48:49], v[64:65], v[52:53], v[48:49] op_sel:[1,0,0] op_sel_hi:[0,1,1]
	ds_read_b128 v[52:55], v152 offset:52224
	ds_read_b128 v[134:137], v152 offset:60416
	v_mov_b32_e32 v57, v58
	v_pk_fma_f32 v[48:49], v[124:125], v[56:57], v[48:49] op_sel_hi:[0,1,1]
	v_mov_b32_e32 v58, v51
	v_pk_fma_f32 v[126:127], v[128:129], v[58:59], v[48:49] op_sel_hi:[0,1,1]
	s_waitcnt lgkmcnt(0)
	v_pk_mov_b32 v[50:51], v[134:135], v[52:53] op_sel:[1,0]
	v_mov_b32_e32 v48, v134
	v_mov_b32_e32 v49, v53
	v_pk_mul_f32 v[50:51], v[64:65], v[50:51] op_sel:[1,0] op_sel_hi:[0,1]
	v_fma_f32 v60, v96, v46, v14
	v_mul_f32_e32 v46, v47, v112
	v_pk_mul_f32 v[44:45], v[44:45], v[112:113] op_sel_hi:[1,0]
	v_pk_fma_f32 v[48:49], v[64:65], v[48:49], v[50:51]
	v_fma_f32 v122, v97, v46, v15
	v_pk_fma_f32 v[134:135], v[104:105], v[44:45], v[12:13]
	v_mov_b32_e32 v50, v136
	v_cvt_pk_bf16_f32 v52, v134, v135
	v_cvt_pk_bf16_f32 v53, v60, v122
	ds_read_b128 v[44:47], v152 offset:4096
	ds_read_b128 v[62:65], v152 offset:12288
	v_mov_b32_e32 v51, v54
	v_pk_fma_f32 v[48:49], v[124:125], v[50:51], v[48:49] op_sel_hi:[0,1,1]
	v_mov_b32_e32 v54, v137
	v_pk_fma_f32 v[124:125], v[128:129], v[54:55], v[48:49] op_sel_hi:[0,1,1]
	s_waitcnt lgkmcnt(0)
	v_pk_mov_b32 v[48:49], v[44:45], v[62:63] op_sel:[1,0]
	v_mov_b32_e32 v45, v63
	global_store_dwordx2 v[110:111], v[52:53], off offset:2048
	v_pk_mul_f32 v[44:45], v[134:135], v[44:45]
	v_mov_b32_e32 v56, v46
	v_pk_fma_f32 v[44:45], v[134:135], v[48:49], v[44:45] op_sel:[1,0,0] op_sel_hi:[0,1,1]
	ds_read_b128 v[48:51], v152 offset:20480
	ds_read_b128 v[52:55], v152 offset:28672
	v_mov_b32_e32 v57, v64
	v_pk_fma_f32 v[212:213], v[60:61], v[56:57], v[44:45] op_sel_hi:[0,1,1]
	v_mov_b32_e32 v64, v47
	v_mul_f32_e32 v42, v42, v112
	s_waitcnt lgkmcnt(0)
	v_pk_mov_b32 v[44:45], v[48:49], v[52:53] op_sel:[1,0]
	v_mov_b32_e32 v49, v53
	v_pk_mul_f32 v[46:47], v[134:135], v[48:49]
	v_mov_b32_e32 v52, v50
	v_pk_fma_f32 v[44:45], v[134:135], v[44:45], v[46:47] op_sel:[1,0,0] op_sel_hi:[0,1,1]
	ds_read_b128 v[56:59], v152 offset:36864
	ds_read_b128 v[46:49], v152 offset:45056
	v_mov_b32_e32 v53, v54
	v_pk_fma_f32 v[148:149], v[60:61], v[52:53], v[44:45] op_sel_hi:[0,1,1]
	v_mov_b32_e32 v54, v51
	s_waitcnt lgkmcnt(1)
	v_mov_b32_e32 v62, v58
	s_waitcnt lgkmcnt(0)
	v_pk_mov_b32 v[44:45], v[56:57], v[46:47] op_sel:[1,0]
	v_mov_b32_e32 v57, v47
	v_pk_mul_f32 v[46:47], v[134:135], v[56:57]
	v_mov_b32_e32 v63, v48
	v_pk_fma_f32 v[56:57], v[134:135], v[44:45], v[46:47] op_sel:[1,0,0] op_sel_hi:[0,1,1]
	ds_read_b128 v[50:53], v152 offset:53248
	ds_read_b128 v[44:47], v152 offset:61440
	v_fma_f32 v130, v86, v42, v10
	v_mul_f32_e32 v42, v43, v112
	v_pk_mul_f32 v[40:41], v[40:41], v[112:113] op_sel_hi:[1,0]
	v_pk_fma_f32 v[136:137], v[60:61], v[62:63], v[56:57] op_sel_hi:[0,1,1]
	v_fma_f32 v128, v87, v42, v11
	v_pk_fma_f32 v[62:63], v[88:89], v[40:41], v[8:9]
	s_waitcnt lgkmcnt(0)
	v_mov_b32_e32 v56, v44
	v_cvt_pk_bf16_f32 v40, v62, v63
	v_cvt_pk_bf16_f32 v41, v130, v128
	ds_read_b128 v[164:167], v152 offset:5120
	ds_read_b128 v[168:171], v152 offset:13312
	v_pk_mov_b32 v[44:45], v[44:45], v[50:51] op_sel:[1,0]
	global_store_dwordx2 v[110:111], v[40:41], off offset:2560
	v_mov_b32_e32 v57, v51
	v_pk_mul_f32 v[44:45], v[134:135], v[44:45] op_sel:[1,0] op_sel_hi:[0,1]
	s_waitcnt lgkmcnt(0)
	v_pk_mov_b32 v[40:41], v[164:165], v[168:169] op_sel:[1,0]
	v_mov_b32_e32 v165, v169
	ds_read_b128 v[172:175], v152 offset:21504
	ds_read_b128 v[176:179], v152 offset:29696
	v_pk_fma_f32 v[44:45], v[134:135], v[56:57], v[44:45]
	v_mov_b32_e32 v50, v46
	v_mov_b32_e32 v51, v52
	v_pk_mul_f32 v[42:43], v[62:63], v[164:165]
	v_mov_b32_e32 v48, v59
	v_pk_fma_f32 v[134:135], v[60:61], v[50:51], v[44:45] op_sel_hi:[0,1,1]
	v_pk_fma_f32 v[164:165], v[62:63], v[40:41], v[42:43] op_sel:[1,0,0] op_sel_hi:[0,1,1]
	ds_read_b128 v[56:59], v152 offset:37888
	ds_read_b128 v[42:45], v152 offset:46080
	s_waitcnt lgkmcnt(2)
	v_pk_mov_b32 v[40:41], v[172:173], v[176:177] op_sel:[1,0]
	v_mov_b32_e32 v173, v177
	v_pk_mul_f32 v[50:51], v[62:63], v[172:173]
	v_mov_b32_e32 v46, v53
	v_pk_fma_f32 v[172:173], v[62:63], v[40:41], v[50:51] op_sel:[1,0,0] op_sel_hi:[0,1,1]
	s_waitcnt lgkmcnt(0)
	v_pk_mov_b32 v[60:61], v[56:57], v[42:43] op_sel:[1,0]
	v_mov_b32_e32 v57, v43
	ds_read_b128 v[50:53], v152 offset:54272
	ds_read_b128 v[40:43], v152 offset:62464
	v_pk_mul_f32 v[56:57], v[62:63], v[56:57]
	v_mul_f32_e32 v38, v38, v112
	v_pk_fma_f32 v[214:215], v[62:63], v[60:61], v[56:57] op_sel:[1,0,0] op_sel_hi:[0,1,1]
	s_waitcnt lgkmcnt(1)
	v_mov_b32_e32 v57, v51
	s_waitcnt lgkmcnt(0)
	v_mov_b32_e32 v56, v40
	v_pk_mov_b32 v[40:41], v[40:41], v[50:51] op_sel:[1,0]
	v_fma_f32 v50, v78, v38, v6
	v_pk_mul_f32 v[40:41], v[62:63], v[40:41] op_sel:[1,0] op_sel_hi:[0,1]
	v_mul_f32_e32 v38, v39, v112
	v_pk_mul_f32 v[36:37], v[36:37], v[112:113] op_sel_hi:[1,0]
	v_pk_fma_f32 v[56:57], v[62:63], v[56:57], v[40:41]
	v_fma_f32 v40, v79, v38, v7
	v_pk_fma_f32 v[140:141], v[82:83], v[36:37], v[4:5]
	v_pk_mul_f32 v[32:33], v[32:33], v[112:113] op_sel_hi:[1,0]
	v_cvt_pk_bf16_f32 v36, v140, v141
	v_cvt_pk_bf16_f32 v37, v50, v40
	ds_read_b128 v[180:183], v152 offset:6144
	ds_read_b128 v[184:187], v152 offset:14336
	global_store_dwordx2 v[110:111], v[36:37], off offset:3072
	ds_read_b128 v[188:191], v152 offset:22528
	ds_read_b128 v[192:195], v152 offset:30720
	v_mov_b32_e32 v168, v166
	v_mov_b32_e32 v169, v170
	s_waitcnt lgkmcnt(3)
	v_mov_b32_e32 v36, v180
	s_waitcnt lgkmcnt(2)
; #define LAS __attribute__((address_space(3)))
; __device__ __forceinline__ unsigned cvt_pk_bf16(float lo, float hi) { unsigned r; asm volatile("v_cvt_pk_bf16_f32 %0, %1, %2" : "=v"(r) : "v"(lo), "v"(hi)); return r; }
; template <bool GATES>
; __device__ __forceinline__ void norm_mod_phase(const Frame& F, const float* src0, const float* src1, const float* nw, int sh_off, int sc_off, int nparts, float* x1out) {
;     ...
;         for (int i = 0; i < 8; ++i) { const int c4 = i * 64 + F.lane;
;             f32x4 h;
; #pragma unroll
;             for (int e = 0; e < 4; ++e) h[e] = (xv[i][e] * rstd) * av[i][e] + shv[i][e];
;             u32x2 pk; pk.x = cvt_pk_bf16(h[0], h[1]); pk.y = cvt_pk_bf16(h[2], h[3]);
;             *(u32x2*)(H + (size_t)r * D + c4 * 4) = pk;
;             if (GATES) {
; #pragma unroll
;                 for (int j = 0; j < 8; ++j) { const f32x4 wv = ((const LAS f32x4*)(wg + j * D))[c4]; g[j] += h[0] * wv[0] + h[1] * wv[1] + h[2] * wv[2] + h[3] * wv[3]; } } }
;         if (GATES) {
; #pragma unroll
;             for (int j = 0; j < 8; ++j) g[j] = wave_sum(g[j]);
	v_mov_b32_e32 v37, v185
	v_pk_fma_f32 v[150:151], v[84:85], v[32:33], v[0:1]
	v_mul_f32_e32 v32, v34, v112
	v_pk_add_f32 v[120:121], v[120:121], v[138:139]
	v_pk_fma_f32 v[64:65], v[122:123], v[64:65], v[212:213] op_sel_hi:[0,1,1]
	v_mov_b32_e32 v142, v52
	v_pk_mul_f32 v[218:219], v[140:141], v[36:37]
	s_waitcnt lgkmcnt(1)
	v_mov_b32_e32 v36, v188
	s_waitcnt lgkmcnt(0)
	v_mov_b32_e32 v37, v193
	v_fma_f32 v52, v80, v32, v2
	v_mul_f32_e32 v32, v35, v112
	v_pk_add_f32 v[64:65], v[120:121], v[64:65]
	v_pk_fma_f32 v[120:121], v[130:131], v[168:169], v[164:165] op_sel_hi:[0,1,1]
	v_mov_b32_e32 v170, v167
	ds_read_b128 v[196:199], v152 offset:38912
	ds_read_b128 v[200:203], v152 offset:47104
	v_pk_mul_f32 v[220:221], v[140:141], v[36:37]
	ds_read_b128 v[60:63], v152 offset:55296
	ds_read_b128 v[36:39], v152 offset:63488
	v_fma_f32 v34, v81, v32, v3
	v_cvt_pk_bf16_f32 v32, v150, v151
	v_cvt_pk_bf16_f32 v33, v52, v34
	ds_read_b128 v[204:207], v152 offset:7168
	ds_read_b128 v[208:211], v152 offset:15360
	v_pk_fma_f32 v[120:121], v[128:129], v[170:171], v[120:121] op_sel_hi:[0,1,1]
	v_pk_add_f32 v[64:65], v[64:65], v[120:121]
	v_pk_mov_b32 v[120:121], v[180:181], v[184:185] op_sel:[1,0]
	v_mov_b32_e32 v138, v182
	v_pk_fma_f32 v[120:121], v[140:141], v[120:121], v[218:219] op_sel:[1,0,0] op_sel_hi:[0,1,1]
	v_mov_b32_e32 v139, v186
	v_pk_fma_f32 v[120:121], v[50:51], v[138:139], v[120:121] op_sel_hi:[0,1,1]
	v_mov_b32_e32 v186, v183
	v_mov_b32_e32 v176, v174
	v_mov_b32_e32 v177, v178
	v_pk_fma_f32 v[120:121], v[40:41], v[186:187], v[120:121] op_sel_hi:[0,1,1]
	v_pk_add_f32 v[118:119], v[118:119], v[132:133]
	v_pk_fma_f32 v[54:55], v[122:123], v[54:55], v[148:149] op_sel_hi:[0,1,1]
	v_pk_add_f32 v[64:65], v[64:65], v[120:121]
	s_waitcnt lgkmcnt(0)
	v_pk_mov_b32 v[120:121], v[204:205], v[208:209] op_sel:[1,0]
	v_mov_b32_e32 v205, v209
	v_pk_add_f32 v[54:55], v[118:119], v[54:55]
	v_pk_fma_f32 v[118:119], v[130:131], v[176:177], v[172:173] op_sel_hi:[0,1,1]
	v_mov_b32_e32 v178, v175
	v_pk_mul_f32 v[138:139], v[150:151], v[204:205]
	ds_read_b128 v[164:167], v152 offset:23552
	ds_read_b128 v[168:171], v152 offset:31744
	v_pk_fma_f32 v[118:119], v[128:129], v[178:179], v[118:119] op_sel_hi:[0,1,1]
	v_pk_fma_f32 v[120:121], v[150:151], v[120:121], v[138:139] op_sel:[1,0,0] op_sel_hi:[0,1,1]
	v_mov_b32_e32 v138, v206
	v_mov_b32_e32 v139, v210
	v_pk_add_f32 v[54:55], v[54:55], v[118:119]
	v_pk_mov_b32 v[118:119], v[188:189], v[192:193] op_sel:[1,0]
	v_pk_fma_f32 v[120:121], v[52:53], v[138:139], v[120:121] op_sel_hi:[0,1,1]
	v_mov_b32_e32 v210, v207
	v_pk_fma_f32 v[118:119], v[140:141], v[118:119], v[220:221] op_sel:[1,0,0] op_sel_hi:[0,1,1]
	v_mov_b32_e32 v132, v190
	v_mov_b32_e32 v133, v194
	v_pk_fma_f32 v[120:121], v[34:35], v[210:211], v[120:121] op_sel_hi:[0,1,1]
	v_pk_fma_f32 v[118:119], v[50:51], v[132:133], v[118:119] op_sel_hi:[0,1,1]
	v_mov_b32_e32 v194, v191
	v_pk_add_f32 v[64:65], v[64:65], v[120:121]
	v_pk_fma_f32 v[118:119], v[40:41], v[194:195], v[118:119] op_sel_hi:[0,1,1]
	ds_bpermute_b32 v120, v113, v64
	ds_bpermute_b32 v121, v113, v65
	v_pk_add_f32 v[54:55], v[54:55], v[118:119]
	s_waitcnt lgkmcnt(2)
	v_pk_mov_b32 v[118:119], v[164:165], v[168:169] op_sel:[1,0]
	v_mov_b32_e32 v165, v169
	v_pk_mul_f32 v[132:133], v[150:151], v[164:165]
	s_waitcnt lgkmcnt(0)
	v_pk_add_f32 v[64:65], v[64:65], v[120:121]
	v_pk_fma_f32 v[118:119], v[150:151], v[118:119], v[132:133] op_sel:[1,0,0] op_sel_hi:[0,1,1]
	v_mov_b32_e32 v132, v166
	v_mov_b32_e32 v133, v170
	v_pk_fma_f32 v[118:119], v[52:53], v[132:133], v[118:119] op_sel_hi:[0,1,1]
	v_mov_b32_e32 v170, v167
	v_pk_fma_f32 v[118:119], v[34:35], v[170:171], v[118:119] op_sel_hi:[0,1,1]
	v_pk_add_f32 v[54:55], v[54:55], v[118:119]
	ds_bpermute_b32 v120, v123, v64
	ds_bpermute_b32 v121, v123, v65
	ds_bpermute_b32 v118, v113, v54
	ds_bpermute_b32 v119, v113, v55
	v_mov_b32_e32 v216, v58
	v_mov_b32_e32 v217, v44
	s_waitcnt lgkmcnt(2)
	v_pk_add_f32 v[64:65], v[64:65], v[120:121]
	ds_bpermute_b32 v120, v129, v64
	s_waitcnt lgkmcnt(1)
	v_pk_add_f32 v[54:55], v[54:55], v[118:119]
	ds_bpermute_b32 v121, v129, v65
	ds_bpermute_b32 v118, v123, v54
	ds_bpermute_b32 v119, v123, v55
	v_pk_add_f32 v[116:117], v[116:117], v[126:127]
	v_pk_fma_f32 v[48:49], v[122:123], v[48:49], v[136:137] op_sel_hi:[0,1,1]
	v_pk_add_f32 v[48:49], v[116:117], v[48:49]
	v_pk_fma_f32 v[116:117], v[130:131], v[216:217], v[214:215] op_sel_hi:[0,1,1]
	v_mov_b32_e32 v44, v59
	v_mov_b32_e32 v222, v196
	v_mov_b32_e32 v223, v201
	s_waitcnt lgkmcnt(2)
	v_pk_add_f32 v[64:65], v[64:65], v[120:121]
	s_waitcnt lgkmcnt(0)
	v_pk_add_f32 v[54:55], v[54:55], v[118:119]
	ds_read_b128 v[118:121], v152 offset:39936
	ds_read_b128 v[164:167], v152 offset:48128
	v_pk_fma_f32 v[44:45], v[128:129], v[44:45], v[116:117] op_sel_hi:[0,1,1]
	v_pk_mul_f32 v[138:139], v[140:141], v[222:223]
	v_pk_add_f32 v[44:45], v[48:49], v[44:45]
	v_pk_mov_b32 v[48:49], v[196:197], v[200:201] op_sel:[1,0]
	ds_bpermute_b32 v168, v129, v54
	ds_bpermute_b32 v169, v129, v55
	v_pk_fma_f32 v[48:49], v[140:141], v[48:49], v[138:139] op_sel:[1,0,0] op_sel_hi:[0,1,1]
	v_mov_b32_e32 v58, v198
	v_mov_b32_e32 v59, v202
	v_pk_fma_f32 v[48:49], v[50:51], v[58:59], v[48:49] op_sel_hi:[0,1,1]
	v_mov_b32_e32 v202, v199
	v_pk_fma_f32 v[48:49], v[40:41], v[202:203], v[48:49] op_sel_hi:[0,1,1]
	v_pk_add_f32 v[44:45], v[44:45], v[48:49]
	s_waitcnt lgkmcnt(2)
; template <bool GATES>
; __device__ __forceinline__ void norm_mod_phase(const Frame& F, const float* src0, const float* src1, const float* nw, int sh_off, int sc_off, int nparts, float* x1out) {
;     ...
;         if (GATES) {
; #pragma unroll
;             for (int j = 0; j < 8; ++j) g[j] = wave_sum(g[j]);
;             if (F.lane == 0) { float* gp = (float*)(F.ws + WS_GATES) + (size_t)r * 8;
;                 *(f32x4*)gp = (f32x4){g[0], g[1], g[2], g[3]}; *(f32x4*)(gp + 4) = (f32x4){g[4], g[5], g[6], g[7]}; } }
;     }
	v_pk_mov_b32 v[48:49], v[118:119], v[164:165] op_sel:[1,0]
	v_mov_b32_e32 v119, v165
	v_mov_b32_e32 v174, v60
	v_mov_b32_e32 v175, v37
	v_pk_mul_f32 v[58:59], v[150:151], v[118:119]
	v_mov_b32_e32 v143, v42
	v_pk_mul_f32 v[132:133], v[140:141], v[174:175]
	s_waitcnt lgkmcnt(0)
	v_pk_add_f32 v[176:177], v[54:55], v[168:169]
	ds_read_b128 v[168:171], v152 offset:56320
	ds_read_b128 v[172:175], v152 offset:64512
	v_pk_fma_f32 v[48:49], v[150:151], v[48:49], v[58:59] op_sel:[1,0,0] op_sel_hi:[0,1,1]
	v_mov_b32_e32 v58, v120
	v_mov_b32_e32 v59, v166
	v_pk_fma_f32 v[48:49], v[52:53], v[58:59], v[48:49] op_sel_hi:[0,1,1]
	v_pk_add_f32 v[58:59], v[114:115], v[124:125]
	v_pk_fma_f32 v[46:47], v[122:123], v[46:47], v[134:135] op_sel:[0,0,1] op_sel_hi:[0,1,0]
	v_pk_fma_f32 v[56:57], v[130:131], v[142:143], v[56:57] op_sel:[0,0,1] op_sel_hi:[0,1,0]
	v_mov_b32_e32 v42, v53
	v_pk_add_f32 v[46:47], v[58:59], v[46:47] op_sel:[1,0] op_sel_hi:[0,1]
	v_pk_fma_f32 v[42:43], v[128:129], v[42:43], v[56:57] op_sel_hi:[0,1,1]
	v_pk_mov_b32 v[36:37], v[60:61], v[36:37] op_sel:[1,0]
	v_pk_add_f32 v[42:43], v[46:47], v[42:43]
	v_pk_fma_f32 v[36:37], v[140:141], v[36:37], v[132:133] op_sel:[1,0,0] op_sel_hi:[0,1,1]
	v_mov_b32_e32 v46, v62
	v_mov_b32_e32 v47, v38
	v_pk_fma_f32 v[36:37], v[50:51], v[46:47], v[36:37] op_sel_hi:[0,1,1]
	v_mov_b32_e32 v38, v63
	v_pk_fma_f32 v[36:37], v[40:41], v[38:39], v[36:37] op_sel_hi:[0,1,1]
	s_waitcnt lgkmcnt(0)
	v_pk_mov_b32 v[38:39], v[168:169], v[172:173] op_sel:[1,0]
	v_mov_b32_e32 v169, v173
	v_pk_mul_f32 v[40:41], v[150:151], v[168:169]
	v_mov_b32_e32 v166, v121
	v_pk_fma_f32 v[38:39], v[150:151], v[38:39], v[40:41] op_sel:[1,0,0] op_sel_hi:[0,1,1]
	v_mov_b32_e32 v40, v170
	v_mov_b32_e32 v41, v174
	v_pk_fma_f32 v[38:39], v[52:53], v[40:41], v[38:39] op_sel_hi:[0,1,1]
	v_mov_b32_e32 v174, v171
	v_pk_fma_f32 v[48:49], v[34:35], v[166:167], v[48:49] op_sel_hi:[0,1,1]
	v_pk_add_f32 v[36:37], v[42:43], v[36:37]
	v_pk_fma_f32 v[34:35], v[34:35], v[174:175], v[38:39] op_sel_hi:[0,1,1]
	v_pk_add_f32 v[44:45], v[44:45], v[48:49]
	v_pk_add_f32 v[34:35], v[36:37], v[34:35]
	ds_bpermute_b32 v148, v131, v64
	ds_bpermute_b32 v149, v131, v65
	ds_bpermute_b32 v48, v113, v44
	ds_bpermute_b32 v49, v113, v45
	ds_bpermute_b32 v36, v113, v34
	ds_bpermute_b32 v37, v113, v35
	s_waitcnt lgkmcnt(4)
	v_pk_add_f32 v[64:65], v[64:65], v[148:149]
	ds_bpermute_b32 v148, v145, v64
	s_waitcnt lgkmcnt(3)
	v_pk_add_f32 v[40:41], v[44:45], v[48:49]
	ds_bpermute_b32 v149, v145, v65
	s_waitcnt lgkmcnt(2)
	v_pk_add_f32 v[34:35], v[34:35], v[36:37]
	ds_bpermute_b32 v178, v131, v176
	ds_bpermute_b32 v179, v131, v177
	ds_bpermute_b32 v42, v123, v40
	ds_bpermute_b32 v43, v123, v41
	ds_bpermute_b32 v36, v123, v34
	ds_bpermute_b32 v37, v123, v35
	s_waitcnt lgkmcnt(6)
	v_pk_add_f32 v[54:55], v[64:65], v[148:149]
	s_waitcnt lgkmcnt(4)
	v_pk_add_f32 v[148:149], v[176:177], v[178:179]
	s_waitcnt lgkmcnt(2)
	v_pk_add_f32 v[40:41], v[40:41], v[42:43]
	ds_bpermute_b32 v38, v145, v148
	s_waitcnt lgkmcnt(1)
	v_pk_add_f32 v[36:37], v[34:35], v[36:37]
	ds_bpermute_b32 v39, v145, v149
	ds_bpermute_b32 v42, v129, v40
	ds_bpermute_b32 v43, v129, v41
	ds_bpermute_b32 v44, v129, v36
	ds_bpermute_b32 v45, v129, v37
	s_waitcnt lgkmcnt(4)
	v_pk_add_f32 v[34:35], v[148:149], v[38:39]
	ds_bpermute_b32 v64, v147, v54
	s_waitcnt lgkmcnt(3)
	v_pk_add_f32 v[38:39], v[40:41], v[42:43]
	ds_bpermute_b32 v40, v131, v38
	s_waitcnt lgkmcnt(2)
	v_pk_add_f32 v[42:43], v[36:37], v[44:45]
	ds_bpermute_b32 v41, v131, v39
	ds_bpermute_b32 v44, v131, v42
	ds_bpermute_b32 v45, v131, v43
	ds_bpermute_b32 v65, v147, v55
	ds_bpermute_b32 v36, v147, v34
	s_waitcnt lgkmcnt(4)
	v_pk_add_f32 v[38:39], v[38:39], v[40:41]
	ds_bpermute_b32 v40, v145, v38
	s_waitcnt lgkmcnt(3)
	v_pk_add_f32 v[42:43], v[42:43], v[44:45]
	ds_bpermute_b32 v41, v145, v39
	ds_bpermute_b32 v44, v145, v42
	ds_bpermute_b32 v45, v145, v43
	ds_bpermute_b32 v37, v147, v35
	global_store_dwordx2 v[110:111], v[32:33], off offset:3584
	s_waitcnt lgkmcnt(3)
	v_pk_add_f32 v[38:39], v[38:39], v[40:41]
	ds_bpermute_b32 v40, v147, v38
	s_waitcnt lgkmcnt(2)
	v_pk_add_f32 v[42:43], v[42:43], v[44:45]
	ds_bpermute_b32 v41, v147, v39
	ds_bpermute_b32 v44, v147, v42
	ds_bpermute_b32 v45, v147, v43
	s_and_saveexec_b64 s[16:17], s[2:3]
	s_cbranch_execz .LBB0_198
	s_add_u32 s18, s84, s12
	s_waitcnt lgkmcnt(4)
	v_pk_add_f32 v[34:35], v[34:35], v[36:37]
	v_pk_add_f32 v[32:33], v[54:55], v[64:65]
	s_addc_u32 s19, s85, s13
	s_waitcnt lgkmcnt(0)
	v_pk_add_f32 v[42:43], v[42:43], v[44:45]
	v_pk_add_f32 v[40:41], v[38:39], v[40:41]
	global_store_dwordx4 v162, v[32:35], s[18:19]
	global_store_dwordx4 v162, v[40:43], s[18:19] offset:16
	s_branch .LBB0_198

; __device__ __forceinline__ unsigned cvt_pk_bf16(float lo, float hi) { unsigned r; asm volatile("v_cvt_pk_bf16_f32 %0, %1, %2" : "=v"(r) : "v"(lo), "v"(hi)); return r; }
; template <bool GATES>
; __device__ __forceinline__ void norm_mod_phase(const Frame& F, const float* src0, const float* src1, const float* nw, int sh_off, int sc_off, int nparts, float* x1out) {
;     ...
;     for (int r = F.bid * 8 + F.wave; r < MTOT; r += F.G * 8) {
;         const float* xr = r < SP ? src0 + (size_t)r * D : src1 + (size_t)(r - SP) * D;
;         f32x4 xv[8]; float ss = 0.f;
; #pragma unroll
;         for (int i = 0; i < 8; ++i) xv[i] = ((const f32x4*)xr)[i * 64 + F.lane];
;         if (r >= SP) { const float* mr = mod + (size_t)((r - SP) >> 2) * NMOD;
; #pragma unroll
;             for (int i = 0; i < 8; ++i) { const int c4 = i * 64 + F.lane; const f32x4 w = ((const f32x4*)nw)[c4], sc = ((const f32x4*)(mr + sc_off))[c4]; shv[i] = ((const f32x4*)(mr + sh_off))[c4]; av[i] = w * (sc + 1.f); }
;             if (nparts > 0) {
;                 for (int z = 0; z < nparts; ++z) { const f32x4* pp = (const f32x4*)(F.ws + WS_PART) + ((size_t)z * MS + (r - SP)) * (D / 4);
; #pragma unroll
;                     for (int i = 0; i < 8; ++i) xv[i] += pp[i * 64 + F.lane]; }
; #pragma unroll
;                 for (int i = 0; i < 8; ++i) ((f32x4*)(x1out + (size_t)(r - SP) * D))[i * 64 + F.lane] = xv[i]; } }
; #pragma unroll
;         for (int i = 0; i < 8; ++i) ss += xv[i][0] * xv[i][0] + xv[i][1] * xv[i][1] + xv[i][2] * xv[i][2] + xv[i][3] * xv[i][3];
;         ss = wave_sum(ss);
;         const float rstd = rsqrtf(ss * (1.f / D) + EPS);
;         float g[8];
; #pragma unroll
;         for (int j = 0; j < 8; ++j) g[j] = 0.f;
; #pragma unroll
;         for (int i = 0; i < 8; ++i) { const int c4 = i * 64 + F.lane;
;             f32x4 h;
; #pragma unroll
;             for (int e = 0; e < 4; ++e) h[e] = (xv[i][e] * rstd) * av[i][e] + shv[i][e];
;             u32x2 pk; pk.x = cvt_pk_bf16(h[0], h[1]); pk.y = cvt_pk_bf16(h[2], h[3]);
;             *(u32x2*)(H + (size_t)r * D + c4 * 4) = pk;
.Lmy_p8_join:
	v_pk_mul_f32 v[128:129], v[60:61], v[60:61]
	v_pk_mul_f32 v[130:131], v[32:33], v[32:33]
	v_add_f32_e32 v133, v133, v142
	v_pk_mul_f32 v[110:111], v[62:63], v[62:63]
	v_pk_mul_f32 v[112:113], v[34:35], v[34:35]
	v_add_f32_e32 v134, v132, v133
	v_mov_b32_e32 v132, v128
	v_mov_b32_e32 v133, v130
	v_mov_b32_e32 v130, v129
	v_pk_add_f32 v[128:129], v[132:133], v[130:131]
	v_mov_b32_e32 v130, v110
	v_mov_b32_e32 v131, v112
	v_pk_add_f32 v[128:129], v[130:131], v[128:129]
	v_mov_b32_e32 v112, v111
	v_pk_add_f32 v[110:111], v[112:113], v[128:129]
	s_add_u32 s2, s2, s6
	v_add_f32_e32 v111, v111, v134
	v_add_f32_e32 v110, v110, v111
	ds_bpermute_b32 v111, v114, v110
	s_addc_u32 s3, s3, s7
	s_cmpk_lt_i32 s2, 0x2000
	s_cbranch_scc0 .Lmy_p8_nopf
	s_lshl_b64 s[52:53], s[2:3], 13
	s_add_u32 s52, s14, s52
	s_addc_u32 s53, s15, s53
	v_lshlrev_b32_e32 v200, 4, v160
	global_load_dwordx4 v[168:171], v200, s[52:53]
	global_load_dwordx4 v[172:175], v200, s[52:53] offset:1024
	global_load_dwordx4 v[176:179], v200, s[52:53] offset:2048
	global_load_dwordx4 v[180:183], v200, s[52:53] offset:3072
	global_load_dwordx4 v[184:187], v120, s[52:53]
	global_load_dwordx4 v[188:191], v121, s[52:53]
	global_load_dwordx4 v[192:195], v122, s[52:53]
	global_load_dwordx4 v[196:199], v123, s[52:53]
.Lmy_p8_nopf:
	s_cmpk_lt_i32 s2, 0x2200
	s_waitcnt lgkmcnt(0)
	v_add_f32_e32 v110, v110, v111
	ds_bpermute_b32 v111, v115, v110
	s_waitcnt lgkmcnt(0)
	v_add_f32_e32 v110, v110, v111
	ds_bpermute_b32 v111, v116, v110
	s_waitcnt lgkmcnt(0)
	v_add_f32_e32 v110, v110, v111
	ds_bpermute_b32 v111, v117, v110
	s_waitcnt lgkmcnt(0)
	v_add_f32_e32 v110, v110, v111
	ds_bpermute_b32 v111, v118, v110
	s_waitcnt lgkmcnt(0)
	v_add_f32_e32 v110, v110, v111
	ds_bpermute_b32 v111, v119, v110
	s_waitcnt lgkmcnt(0)
	v_add_f32_e32 v110, v110, v111
	v_fmamk_f32 v110, v110, 0x3a000000, v127
	v_mul_f32_e32 v111, 0x4b800000, v110
	v_cmp_gt_f32_e32 vcc, s19, v110
	s_nop 1
	v_cndmask_b32_e32 v110, v110, v111, vcc
	v_rsq_f32_e32 v110, v110
	s_nop 0
	v_mul_f32_e32 v111, 0x45800000, v110
	v_cndmask_b32_e32 v110, v110, v111, vcc
	v_mul_f32_e32 v56, v56, v110
	v_mul_f32_e32 v57, v57, v110
	v_mul_f32_e32 v52, v52, v110
	v_mul_f32_e32 v53, v53, v110
	v_mul_f32_e32 v48, v48, v110
	v_mul_f32_e32 v49, v49, v110
	v_mul_f32_e32 v44, v44, v110
	v_mul_f32_e32 v45, v45, v110
	v_mul_f32_e32 v40, v40, v110
	v_mul_f32_e32 v41, v41, v110
	v_mul_f32_e32 v36, v36, v110
	v_mul_f32_e32 v37, v37, v110
	v_mul_f32_e32 v32, v32, v110
	v_mul_f32_e32 v33, v33, v110
	v_fma_f32 v56, v78, v56, v0
	v_fma_f32 v57, v79, v57, v1
	v_mul_f32_e32 v58, v58, v110
	v_mul_f32_e32 v59, v59, v110
	v_fma_f32 v52, v84, v52, v4
	v_fma_f32 v53, v85, v53, v5
	v_mul_f32_e32 v54, v54, v110
	v_mul_f32_e32 v55, v55, v110
	v_fma_f32 v48, v88, v48, v8
	v_fma_f32 v49, v89, v49, v9
	v_mul_f32_e32 v50, v50, v110
	v_mul_f32_e32 v51, v51, v110
	v_fma_f32 v44, v92, v44, v20
	v_fma_f32 v45, v93, v45, v21
	v_mul_f32_e32 v46, v46, v110
	v_mul_f32_e32 v47, v47, v110
	v_fma_f32 v40, v96, v40, v16
	v_fma_f32 v41, v97, v41, v17
	v_mul_f32_e32 v42, v42, v110
	v_mul_f32_e32 v43, v43, v110
	v_fma_f32 v36, v100, v36, v24
	v_fma_f32 v37, v101, v37, v25
	v_mul_f32_e32 v38, v38, v110
	v_mul_f32_e32 v39, v39, v110
	v_fma_f32 v32, v104, v32, v28
	v_fma_f32 v33, v105, v33, v29
	v_mul_f32_e32 v34, v34, v110
	v_mul_f32_e32 v35, v35, v110
	v_fma_f32 v58, v76, v58, v2
	v_fma_f32 v59, v77, v59, v3
	v_cvt_pk_bf16_f32 v56, v56, v57
	v_cvt_pk_bf16_f32 v57, v58, v59
	global_store_dwordx2 v[80:81], v[56:57], off
	v_fma_f32 v54, v82, v54, v6
	v_fma_f32 v55, v83, v55, v7
	v_cvt_pk_bf16_f32 v52, v52, v53
	v_cvt_pk_bf16_f32 v53, v54, v55
	global_store_dwordx2 v[80:81], v[52:53], off offset:512
	v_fma_f32 v50, v86, v50, v10
	v_fma_f32 v51, v87, v51, v11
	v_cvt_pk_bf16_f32 v48, v48, v49
	v_cvt_pk_bf16_f32 v49, v50, v51
	global_store_dwordx2 v[80:81], v[48:49], off offset:1024
	v_fma_f32 v46, v90, v46, v22
	v_fma_f32 v47, v91, v47, v23
	v_cvt_pk_bf16_f32 v44, v44, v45
	v_cvt_pk_bf16_f32 v45, v46, v47
	global_store_dwordx2 v[80:81], v[44:45], off offset:1536
	v_fma_f32 v42, v94, v42, v18
	v_fma_f32 v43, v95, v43, v19
	v_cvt_pk_bf16_f32 v40, v40, v41
	v_cvt_pk_bf16_f32 v41, v42, v43
	global_store_dwordx2 v[80:81], v[40:41], off offset:2048
	v_fma_f32 v38, v98, v38, v26
	v_fma_f32 v39, v99, v39, v27
	v_cvt_pk_bf16_f32 v36, v36, v37
	v_cvt_pk_bf16_f32 v37, v38, v39
	global_store_dwordx2 v[80:81], v[36:37], off offset:2560
	v_fma_f32 v34, v102, v34, v30
	v_fma_f32 v35, v103, v35, v31
	v_cvt_pk_bf16_f32 v32, v32, v33
	v_cvt_pk_bf16_f32 v33, v34, v35
	global_store_dwordx2 v[80:81], v[32:33], off offset:3072
	v_mul_f32_e32 v32, v60, v110
	v_mul_f32_e32 v33, v61, v110
	v_fma_f32 v32, v108, v32, v12
	v_fma_f32 v33, v109, v33, v13
	v_mul_f32_e32 v34, v62, v110
	v_mul_f32_e32 v35, v63, v110
	v_fma_f32 v34, v106, v34, v14
	v_fma_f32 v35, v107, v35, v15
	v_cvt_pk_bf16_f32 v32, v32, v33
	v_cvt_pk_bf16_f32 v33, v34, v35
	global_store_dwordx2 v[80:81], v[32:33], off offset:3584
	v_lshl_add_u64 v[80:81], v[80:81], 0, s[8:9]
	s_cbranch_scc0 .LBB0_968
	s_cmpk_lt_i32 s2, 0x2000
	s_cbranch_scc0 .LBB0_966
	s_waitcnt vmcnt(8)
	v_mov_b32_e32 v56, v168
	v_mov_b32_e32 v57, v169
	v_mov_b32_e32 v58, v170
	v_mov_b32_e32 v59, v171
	v_mov_b32_e32 v52, v172
	v_mov_b32_e32 v53, v173
	v_mov_b32_e32 v54, v174
	v_mov_b32_e32 v55, v175
	v_mov_b32_e32 v48, v176
	v_mov_b32_e32 v49, v177
	v_mov_b32_e32 v50, v178
	v_mov_b32_e32 v51, v179
	v_mov_b32_e32 v44, v180
	v_mov_b32_e32 v45, v181
	v_mov_b32_e32 v46, v182
	v_mov_b32_e32 v47, v183
	v_mov_b32_e32 v40, v184
	v_mov_b32_e32 v41, v185
	v_mov_b32_e32 v42, v186
	v_mov_b32_e32 v43, v187
	v_mov_b32_e32 v36, v188
	v_mov_b32_e32 v37, v189
	v_mov_b32_e32 v38, v190
	v_mov_b32_e32 v39, v191
	v_mov_b32_e32 v32, v192
	v_mov_b32_e32 v33, v193
	v_mov_b32_e32 v34, v194
	v_mov_b32_e32 v35, v195
	v_mov_b32_e32 v60, v196
	v_mov_b32_e32 v61, v197
	v_mov_b32_e32 v62, v198
	v_mov_b32_e32 v63, v199
	v_mul_f32_e32 v110, v57, v57
	v_mul_f32_e32 v111, v53, v53
	v_fmac_f32_e32 v110, v56, v56
	v_fmac_f32_e32 v111, v52, v52
	v_fmac_f32_e32 v110, v58, v58
	v_fmac_f32_e32 v111, v54, v54
	v_fmac_f32_e32 v110, v59, v59
	v_fmac_f32_e32 v111, v55, v55
	v_add_f32_e32 v110, v110, v111
	v_mul_f32_e32 v111, v49, v49
	v_fmac_f32_e32 v111, v48, v48
	v_fmac_f32_e32 v111, v50, v50
	v_fmac_f32_e32 v111, v51, v51
	v_add_f32_e32 v110, v111, v110
	v_mul_f32_e32 v111, v45, v45
	v_pk_mul_f32 v[136:137], v[36:37], v[36:37]
	v_pk_mul_f32 v[138:139], v[40:41], v[40:41]
	v_fmac_f32_e32 v111, v44, v44
	v_pk_mul_f32 v[132:133], v[38:39], v[38:39]
	v_pk_mul_f32 v[134:135], v[42:43], v[42:43]
	v_mov_b32_e32 v140, v136
	v_mov_b32_e32 v141, v138
	v_mov_b32_e32 v138, v137
	v_fmac_f32_e32 v111, v46, v46
	v_pk_add_f32 v[136:137], v[140:141], v[138:139]
	v_mov_b32_e32 v138, v132
	v_mov_b32_e32 v139, v134
	v_fmac_f32_e32 v111, v47, v47
	v_pk_add_f32 v[136:137], v[138:139], v[136:137]
	v_mov_b32_e32 v134, v133
	v_add_f32_e32 v142, v111, v110
	v_pk_add_f32 v[132:133], v[134:135], v[136:137]
	s_branch .Lmy_p8_join
